# v38 + vstat phase rewritten: 8 rows per trip, loads issued together, butterfly steps of 8 rows share each LDS round trip
# speedup vs baseline: 1.0137x; 1.0006x over previous
.LBB0_577:
	v_readlane_b32 s100, v252, 8
	v_readlane_b32 s101, v252, 9
	s_nop 1
	global_load_dwordx2 v[20:21], v[2:3], off nt
	v_lshl_add_u64 v[14:15], v[2:3], 0, s[100:101]
	global_load_dwordx2 v[22:23], v[14:15], off nt
	v_lshl_add_u64 v[14:15], v[14:15], 0, s[100:101]
	global_load_dwordx2 v[24:25], v[14:15], off nt
	v_lshl_add_u64 v[14:15], v[14:15], 0, s[100:101]
	global_load_dwordx2 v[26:27], v[14:15], off nt
	v_lshl_add_u64 v[14:15], v[14:15], 0, s[100:101]
	global_load_dwordx2 v[28:29], v[14:15], off nt
	v_lshl_add_u64 v[14:15], v[14:15], 0, s[100:101]
	global_load_dwordx2 v[30:31], v[14:15], off nt
	v_lshl_add_u64 v[14:15], v[14:15], 0, s[100:101]
	global_load_dwordx2 v[32:33], v[14:15], off nt
	v_lshl_add_u64 v[14:15], v[14:15], 0, s[100:101]
	global_load_dwordx2 v[34:35], v[14:15], off nt
	v_lshl_add_u64 v[2:3], v[14:15], 0, s[100:101]
	s_waitcnt vmcnt(0)
	ds_bpermute_b32 v36, v8, v20
	ds_bpermute_b32 v37, v8, v21
	ds_bpermute_b32 v38, v8, v22
	ds_bpermute_b32 v39, v8, v23
	ds_bpermute_b32 v40, v8, v24
	ds_bpermute_b32 v41, v8, v25
	ds_bpermute_b32 v42, v8, v26
	ds_bpermute_b32 v43, v8, v27
	s_waitcnt lgkmcnt(0)
	v_pk_add_f32 v[20:21], v[20:21], v[36:37]
	v_pk_add_f32 v[22:23], v[22:23], v[38:39]
	v_pk_add_f32 v[24:25], v[24:25], v[40:41]
	v_pk_add_f32 v[26:27], v[26:27], v[42:43]
	ds_bpermute_b32 v44, v8, v28
	ds_bpermute_b32 v45, v8, v29
	ds_bpermute_b32 v46, v8, v30
	ds_bpermute_b32 v47, v8, v31
	ds_bpermute_b32 v48, v8, v32
	ds_bpermute_b32 v49, v8, v33
	ds_bpermute_b32 v50, v8, v34
	ds_bpermute_b32 v51, v8, v35
	s_waitcnt lgkmcnt(0)
	v_pk_add_f32 v[28:29], v[28:29], v[44:45]
	v_pk_add_f32 v[30:31], v[30:31], v[46:47]
	v_pk_add_f32 v[32:33], v[32:33], v[48:49]
	v_pk_add_f32 v[34:35], v[34:35], v[50:51]
	ds_bpermute_b32 v36, v9, v20
	ds_bpermute_b32 v37, v9, v21
	ds_bpermute_b32 v38, v9, v22
	ds_bpermute_b32 v39, v9, v23
	ds_bpermute_b32 v40, v9, v24
	ds_bpermute_b32 v41, v9, v25
	ds_bpermute_b32 v42, v9, v26
	ds_bpermute_b32 v43, v9, v27
	s_waitcnt lgkmcnt(0)
	v_pk_add_f32 v[20:21], v[20:21], v[36:37]
	v_pk_add_f32 v[22:23], v[22:23], v[38:39]
	v_pk_add_f32 v[24:25], v[24:25], v[40:41]
	v_pk_add_f32 v[26:27], v[26:27], v[42:43]
	ds_bpermute_b32 v44, v9, v28
	ds_bpermute_b32 v45, v9, v29
	ds_bpermute_b32 v46, v9, v30
	ds_bpermute_b32 v47, v9, v31
	ds_bpermute_b32 v48, v9, v32
	ds_bpermute_b32 v49, v9, v33
	ds_bpermute_b32 v50, v9, v34
	ds_bpermute_b32 v51, v9, v35
	s_waitcnt lgkmcnt(0)
	v_pk_add_f32 v[28:29], v[28:29], v[44:45]
	v_pk_add_f32 v[30:31], v[30:31], v[46:47]
	v_pk_add_f32 v[32:33], v[32:33], v[48:49]
	v_pk_add_f32 v[34:35], v[34:35], v[50:51]
	ds_bpermute_b32 v36, v10, v20
	ds_bpermute_b32 v37, v10, v21
	ds_bpermute_b32 v38, v10, v22
	ds_bpermute_b32 v39, v10, v23
	ds_bpermute_b32 v40, v10, v24
	ds_bpermute_b32 v41, v10, v25
	ds_bpermute_b32 v42, v10, v26
	ds_bpermute_b32 v43, v10, v27
	s_waitcnt lgkmcnt(0)
	v_pk_add_f32 v[20:21], v[20:21], v[36:37]
	v_pk_add_f32 v[22:23], v[22:23], v[38:39]
	v_pk_add_f32 v[24:25], v[24:25], v[40:41]
	v_pk_add_f32 v[26:27], v[26:27], v[42:43]
	ds_bpermute_b32 v44, v10, v28
	ds_bpermute_b32 v45, v10, v29
	ds_bpermute_b32 v46, v10, v30
	ds_bpermute_b32 v47, v10, v31
	ds_bpermute_b32 v48, v10, v32
	ds_bpermute_b32 v49, v10, v33
	ds_bpermute_b32 v50, v10, v34
	ds_bpermute_b32 v51, v10, v35
	s_waitcnt lgkmcnt(0)
	v_pk_add_f32 v[28:29], v[28:29], v[44:45]
	v_pk_add_f32 v[30:31], v[30:31], v[46:47]
	v_pk_add_f32 v[32:33], v[32:33], v[48:49]
	v_pk_add_f32 v[34:35], v[34:35], v[50:51]
	ds_bpermute_b32 v36, v11, v20
	ds_bpermute_b32 v37, v11, v21
	ds_bpermute_b32 v38, v11, v22
	ds_bpermute_b32 v39, v11, v23
	ds_bpermute_b32 v40, v11, v24
	ds_bpermute_b32 v41, v11, v25
	ds_bpermute_b32 v42, v11, v26
	ds_bpermute_b32 v43, v11, v27
	s_waitcnt lgkmcnt(0)
	v_pk_add_f32 v[20:21], v[20:21], v[36:37]
	v_pk_add_f32 v[22:23], v[22:23], v[38:39]
	v_pk_add_f32 v[24:25], v[24:25], v[40:41]
	v_pk_add_f32 v[26:27], v[26:27], v[42:43]
	ds_bpermute_b32 v44, v11, v28
	ds_bpermute_b32 v45, v11, v29
	ds_bpermute_b32 v46, v11, v30
	ds_bpermute_b32 v47, v11, v31
	ds_bpermute_b32 v48, v11, v32
	ds_bpermute_b32 v49, v11, v33
	ds_bpermute_b32 v50, v11, v34
	ds_bpermute_b32 v51, v11, v35
	s_waitcnt lgkmcnt(0)
	v_pk_add_f32 v[28:29], v[28:29], v[44:45]
	v_pk_add_f32 v[30:31], v[30:31], v[46:47]
	v_pk_add_f32 v[32:33], v[32:33], v[48:49]
	v_pk_add_f32 v[34:35], v[34:35], v[50:51]
	ds_bpermute_b32 v36, v12, v20
	ds_bpermute_b32 v37, v12, v21
	ds_bpermute_b32 v38, v12, v22
	ds_bpermute_b32 v39, v12, v23
	ds_bpermute_b32 v40, v12, v24
	ds_bpermute_b32 v41, v12, v25
	ds_bpermute_b32 v42, v12, v26
	ds_bpermute_b32 v43, v12, v27
	s_waitcnt lgkmcnt(0)
	v_pk_add_f32 v[20:21], v[20:21], v[36:37]
	v_pk_add_f32 v[22:23], v[22:23], v[38:39]
	v_pk_add_f32 v[24:25], v[24:25], v[40:41]
	v_pk_add_f32 v[26:27], v[26:27], v[42:43]
	ds_bpermute_b32 v44, v12, v28
	ds_bpermute_b32 v45, v12, v29
	ds_bpermute_b32 v46, v12, v30
	ds_bpermute_b32 v47, v12, v31
	ds_bpermute_b32 v48, v12, v32
	ds_bpermute_b32 v49, v12, v33
	ds_bpermute_b32 v50, v12, v34
	ds_bpermute_b32 v51, v12, v35
	s_waitcnt lgkmcnt(0)
	v_pk_add_f32 v[28:29], v[28:29], v[44:45]
	v_pk_add_f32 v[30:31], v[30:31], v[46:47]
	v_pk_add_f32 v[32:33], v[32:33], v[48:49]
	v_pk_add_f32 v[34:35], v[34:35], v[50:51]
	ds_bpermute_b32 v36, v13, v20
	ds_bpermute_b32 v37, v13, v21
	ds_bpermute_b32 v38, v13, v22
	ds_bpermute_b32 v39, v13, v23
	ds_bpermute_b32 v40, v13, v24
	ds_bpermute_b32 v41, v13, v25
	ds_bpermute_b32 v42, v13, v26
	ds_bpermute_b32 v43, v13, v27
	s_waitcnt lgkmcnt(0)
	v_pk_add_f32 v[20:21], v[20:21], v[36:37]
	v_pk_add_f32 v[22:23], v[22:23], v[38:39]
	v_pk_add_f32 v[24:25], v[24:25], v[40:41]
	v_pk_add_f32 v[26:27], v[26:27], v[42:43]
	ds_bpermute_b32 v44, v13, v28
	ds_bpermute_b32 v45, v13, v29
	ds_bpermute_b32 v46, v13, v30
	ds_bpermute_b32 v47, v13, v31
	ds_bpermute_b32 v48, v13, v32
	ds_bpermute_b32 v49, v13, v33
	ds_bpermute_b32 v50, v13, v34
	ds_bpermute_b32 v51, v13, v35
	s_waitcnt lgkmcnt(0)
	v_pk_add_f32 v[28:29], v[28:29], v[44:45]
	v_pk_add_f32 v[30:31], v[30:31], v[46:47]
	v_pk_add_f32 v[32:33], v[32:33], v[48:49]
	v_pk_add_f32 v[34:35], v[34:35], v[50:51]
	s_cmpk_lt_i32 s0, 0x4200
	s_cbranch_scc0 .LBB0_579
	s_and_saveexec_b64 s[8:9], s[2:3]
	v_mov_b32_e32 v4, v20
	v_mov_b32_e32 v5, v21
	s_mov_b32 s4, 0x39800000
	v_pk_mul_f32 v[4:5], v[4:5], s[4:5] op_sel_hi:[1,0]
	s_mov_b32 s1, 0xf800000
	v_fma_f32 v5, -v4, v4, v5
	v_add_f32_e32 v5, 0x358637bd, v5
	v_mul_f32_e32 v6, 0x4f800000, v5
	v_cmp_gt_f32_e32 vcc, s1, v5
	s_nop 1
	v_cndmask_b32_e32 v5, v5, v6, vcc
	v_sqrt_f32_e32 v6, v5
	s_nop 0
	v_add_u32_e32 v7, -1, v6
	v_fma_f32 v15, -v7, v6, v5
	v_add_u32_e32 v14, 1, v6
	v_cmp_ge_f32_e64 s[4:5], 0, v15
	s_nop 1
	v_cndmask_b32_e64 v7, v6, v7, s[4:5]
	v_fma_f32 v6, -v14, v6, v5
	v_cmp_lt_f32_e64 s[4:5], 0, v6
	s_nop 1
	v_cndmask_b32_e64 v6, v7, v14, s[4:5]
	v_mul_f32_e32 v7, 0x37800000, v6
	v_cndmask_b32_e32 v6, v6, v7, vcc
	v_cmp_class_f32_e32 vcc, v5, v0
	s_nop 1
	v_cndmask_b32_e32 v5, v6, v5, vcc
	v_div_scale_f32 v6, s[4:5], v5, v5, 1.0
	v_rcp_f32_e32 v7, v6
	s_nop 0
	v_fma_f32 v14, -v6, v7, 1.0
	v_fmac_f32_e32 v7, v14, v7
	v_div_scale_f32 v14, vcc, 1.0, v5, 1.0
	v_mul_f32_e32 v15, v14, v7
	v_fma_f32 v16, -v6, v15, v14
	v_fmac_f32_e32 v15, v16, v7
	v_fma_f32 v6, -v6, v15, v14
	v_div_fmas_f32 v6, v6, v7, v15
	v_div_fixup_f32 v5, v6, v5, 1.0
	global_store_dwordx2 v203, v[4:5], s[6:7]
	s_or_b64 exec, exec, s[8:9]
	s_add_i32 s0, s0, s94
	v_readlane_b32 s4, v252, 28
	v_readlane_b32 s5, v252, 29
	s_nop 1
	s_add_u32 s6, s6, s4
	s_addc_u32 s7, s7, s5
	s_cmpk_lt_i32 s0, 0x4200
	s_cbranch_scc0 .LBB0_579
	s_and_saveexec_b64 s[8:9], s[2:3]
	v_mov_b32_e32 v4, v22
	v_mov_b32_e32 v5, v23
	s_mov_b32 s4, 0x39800000
	v_pk_mul_f32 v[4:5], v[4:5], s[4:5] op_sel_hi:[1,0]
	s_mov_b32 s1, 0xf800000
	v_fma_f32 v5, -v4, v4, v5
	v_add_f32_e32 v5, 0x358637bd, v5
	v_mul_f32_e32 v6, 0x4f800000, v5
	v_cmp_gt_f32_e32 vcc, s1, v5
	s_nop 1
	v_cndmask_b32_e32 v5, v5, v6, vcc
	v_sqrt_f32_e32 v6, v5
	s_nop 0
	v_add_u32_e32 v7, -1, v6
	v_fma_f32 v15, -v7, v6, v5
	v_add_u32_e32 v14, 1, v6
	v_cmp_ge_f32_e64 s[4:5], 0, v15
	s_nop 1
	v_cndmask_b32_e64 v7, v6, v7, s[4:5]
	v_fma_f32 v6, -v14, v6, v5
	v_cmp_lt_f32_e64 s[4:5], 0, v6
	s_nop 1
	v_cndmask_b32_e64 v6, v7, v14, s[4:5]
	v_mul_f32_e32 v7, 0x37800000, v6
	v_cndmask_b32_e32 v6, v6, v7, vcc
	v_cmp_class_f32_e32 vcc, v5, v0
	s_nop 1
	v_cndmask_b32_e32 v5, v6, v5, vcc
	v_div_scale_f32 v6, s[4:5], v5, v5, 1.0
	v_rcp_f32_e32 v7, v6
	s_nop 0
	v_fma_f32 v14, -v6, v7, 1.0
	v_fmac_f32_e32 v7, v14, v7
	v_div_scale_f32 v14, vcc, 1.0, v5, 1.0
	v_mul_f32_e32 v15, v14, v7
	v_fma_f32 v16, -v6, v15, v14
	v_fmac_f32_e32 v15, v16, v7
	v_fma_f32 v6, -v6, v15, v14
	v_div_fmas_f32 v6, v6, v7, v15
	v_div_fixup_f32 v5, v6, v5, 1.0
	global_store_dwordx2 v203, v[4:5], s[6:7]
	s_or_b64 exec, exec, s[8:9]
	s_add_i32 s0, s0, s94
	v_readlane_b32 s4, v252, 28
	v_readlane_b32 s5, v252, 29
	s_nop 1
	s_add_u32 s6, s6, s4
	s_addc_u32 s7, s7, s5
	s_cmpk_lt_i32 s0, 0x4200
	s_cbranch_scc0 .LBB0_579
	s_and_saveexec_b64 s[8:9], s[2:3]
	v_mov_b32_e32 v4, v24
	v_mov_b32_e32 v5, v25
	s_mov_b32 s4, 0x39800000
	v_pk_mul_f32 v[4:5], v[4:5], s[4:5] op_sel_hi:[1,0]
	s_mov_b32 s1, 0xf800000
	v_fma_f32 v5, -v4, v4, v5
	v_add_f32_e32 v5, 0x358637bd, v5
	v_mul_f32_e32 v6, 0x4f800000, v5
	v_cmp_gt_f32_e32 vcc, s1, v5
	s_nop 1
	v_cndmask_b32_e32 v5, v5, v6, vcc
	v_sqrt_f32_e32 v6, v5
	s_nop 0
	v_add_u32_e32 v7, -1, v6
	v_fma_f32 v15, -v7, v6, v5
	v_add_u32_e32 v14, 1, v6
	v_cmp_ge_f32_e64 s[4:5], 0, v15
	s_nop 1
	v_cndmask_b32_e64 v7, v6, v7, s[4:5]
	v_fma_f32 v6, -v14, v6, v5
	v_cmp_lt_f32_e64 s[4:5], 0, v6
	s_nop 1
	v_cndmask_b32_e64 v6, v7, v14, s[4:5]
	v_mul_f32_e32 v7, 0x37800000, v6
	v_cndmask_b32_e32 v6, v6, v7, vcc
	v_cmp_class_f32_e32 vcc, v5, v0
	s_nop 1
	v_cndmask_b32_e32 v5, v6, v5, vcc
	v_div_scale_f32 v6, s[4:5], v5, v5, 1.0
	v_rcp_f32_e32 v7, v6
	s_nop 0
	v_fma_f32 v14, -v6, v7, 1.0
	v_fmac_f32_e32 v7, v14, v7
	v_div_scale_f32 v14, vcc, 1.0, v5, 1.0
	v_mul_f32_e32 v15, v14, v7
	v_fma_f32 v16, -v6, v15, v14
	v_fmac_f32_e32 v15, v16, v7
	v_fma_f32 v6, -v6, v15, v14
	v_div_fmas_f32 v6, v6, v7, v15
	v_div_fixup_f32 v5, v6, v5, 1.0
	global_store_dwordx2 v203, v[4:5], s[6:7]
	s_or_b64 exec, exec, s[8:9]
	s_add_i32 s0, s0, s94
	v_readlane_b32 s4, v252, 28
	v_readlane_b32 s5, v252, 29
	s_nop 1
	s_add_u32 s6, s6, s4
	s_addc_u32 s7, s7, s5
	s_cmpk_lt_i32 s0, 0x4200
	s_cbranch_scc0 .LBB0_579
	s_and_saveexec_b64 s[8:9], s[2:3]
	v_mov_b32_e32 v4, v26
	v_mov_b32_e32 v5, v27
	s_mov_b32 s4, 0x39800000
	v_pk_mul_f32 v[4:5], v[4:5], s[4:5] op_sel_hi:[1,0]
	s_mov_b32 s1, 0xf800000
	v_fma_f32 v5, -v4, v4, v5
	v_add_f32_e32 v5, 0x358637bd, v5
	v_mul_f32_e32 v6, 0x4f800000, v5
	v_cmp_gt_f32_e32 vcc, s1, v5
	s_nop 1
	v_cndmask_b32_e32 v5, v5, v6, vcc
	v_sqrt_f32_e32 v6, v5
	s_nop 0
	v_add_u32_e32 v7, -1, v6
	v_fma_f32 v15, -v7, v6, v5
	v_add_u32_e32 v14, 1, v6
	v_cmp_ge_f32_e64 s[4:5], 0, v15
	s_nop 1
	v_cndmask_b32_e64 v7, v6, v7, s[4:5]
	v_fma_f32 v6, -v14, v6, v5
	v_cmp_lt_f32_e64 s[4:5], 0, v6
	s_nop 1
	v_cndmask_b32_e64 v6, v7, v14, s[4:5]
	v_mul_f32_e32 v7, 0x37800000, v6
	v_cndmask_b32_e32 v6, v6, v7, vcc
	v_cmp_class_f32_e32 vcc, v5, v0
	s_nop 1
	v_cndmask_b32_e32 v5, v6, v5, vcc
	v_div_scale_f32 v6, s[4:5], v5, v5, 1.0
	v_rcp_f32_e32 v7, v6
	s_nop 0
	v_fma_f32 v14, -v6, v7, 1.0
	v_fmac_f32_e32 v7, v14, v7
	v_div_scale_f32 v14, vcc, 1.0, v5, 1.0
	v_mul_f32_e32 v15, v14, v7
	v_fma_f32 v16, -v6, v15, v14
	v_fmac_f32_e32 v15, v16, v7
	v_fma_f32 v6, -v6, v15, v14
	v_div_fmas_f32 v6, v6, v7, v15
	v_div_fixup_f32 v5, v6, v5, 1.0
	global_store_dwordx2 v203, v[4:5], s[6:7]
	s_or_b64 exec, exec, s[8:9]
	s_add_i32 s0, s0, s94
	v_readlane_b32 s4, v252, 28
	v_readlane_b32 s5, v252, 29
	s_nop 1
	s_add_u32 s6, s6, s4
	s_addc_u32 s7, s7, s5
	s_cmpk_lt_i32 s0, 0x4200
	s_cbranch_scc0 .LBB0_579
	s_and_saveexec_b64 s[8:9], s[2:3]
	v_mov_b32_e32 v4, v28
	v_mov_b32_e32 v5, v29
	s_mov_b32 s4, 0x39800000
	v_pk_mul_f32 v[4:5], v[4:5], s[4:5] op_sel_hi:[1,0]
	s_mov_b32 s1, 0xf800000
	v_fma_f32 v5, -v4, v4, v5
	v_add_f32_e32 v5, 0x358637bd, v5
	v_mul_f32_e32 v6, 0x4f800000, v5
	v_cmp_gt_f32_e32 vcc, s1, v5
	s_nop 1
	v_cndmask_b32_e32 v5, v5, v6, vcc
	v_sqrt_f32_e32 v6, v5
	s_nop 0
	v_add_u32_e32 v7, -1, v6
	v_fma_f32 v15, -v7, v6, v5
	v_add_u32_e32 v14, 1, v6
	v_cmp_ge_f32_e64 s[4:5], 0, v15
	s_nop 1
	v_cndmask_b32_e64 v7, v6, v7, s[4:5]
	v_fma_f32 v6, -v14, v6, v5
	v_cmp_lt_f32_e64 s[4:5], 0, v6
	s_nop 1
	v_cndmask_b32_e64 v6, v7, v14, s[4:5]
	v_mul_f32_e32 v7, 0x37800000, v6
	v_cndmask_b32_e32 v6, v6, v7, vcc
	v_cmp_class_f32_e32 vcc, v5, v0
	s_nop 1
	v_cndmask_b32_e32 v5, v6, v5, vcc
	v_div_scale_f32 v6, s[4:5], v5, v5, 1.0
	v_rcp_f32_e32 v7, v6
	s_nop 0
	v_fma_f32 v14, -v6, v7, 1.0
	v_fmac_f32_e32 v7, v14, v7
	v_div_scale_f32 v14, vcc, 1.0, v5, 1.0
	v_mul_f32_e32 v15, v14, v7
	v_fma_f32 v16, -v6, v15, v14
	v_fmac_f32_e32 v15, v16, v7
	v_fma_f32 v6, -v6, v15, v14
	v_div_fmas_f32 v6, v6, v7, v15
	v_div_fixup_f32 v5, v6, v5, 1.0
	global_store_dwordx2 v203, v[4:5], s[6:7]
	s_or_b64 exec, exec, s[8:9]
	s_add_i32 s0, s0, s94
	v_readlane_b32 s4, v252, 28
	v_readlane_b32 s5, v252, 29
	s_nop 1
	s_add_u32 s6, s6, s4
	s_addc_u32 s7, s7, s5
	s_cmpk_lt_i32 s0, 0x4200
	s_cbranch_scc0 .LBB0_579
	s_and_saveexec_b64 s[8:9], s[2:3]
	v_mov_b32_e32 v4, v30
	v_mov_b32_e32 v5, v31
	s_mov_b32 s4, 0x39800000
	v_pk_mul_f32 v[4:5], v[4:5], s[4:5] op_sel_hi:[1,0]
	s_mov_b32 s1, 0xf800000
	v_fma_f32 v5, -v4, v4, v5
	v_add_f32_e32 v5, 0x358637bd, v5
	v_mul_f32_e32 v6, 0x4f800000, v5
	v_cmp_gt_f32_e32 vcc, s1, v5
	s_nop 1
	v_cndmask_b32_e32 v5, v5, v6, vcc
	v_sqrt_f32_e32 v6, v5
	s_nop 0
	v_add_u32_e32 v7, -1, v6
	v_fma_f32 v15, -v7, v6, v5
	v_add_u32_e32 v14, 1, v6
	v_cmp_ge_f32_e64 s[4:5], 0, v15
	s_nop 1
	v_cndmask_b32_e64 v7, v6, v7, s[4:5]
	v_fma_f32 v6, -v14, v6, v5
	v_cmp_lt_f32_e64 s[4:5], 0, v6
	s_nop 1
	v_cndmask_b32_e64 v6, v7, v14, s[4:5]
	v_mul_f32_e32 v7, 0x37800000, v6
	v_cndmask_b32_e32 v6, v6, v7, vcc
	v_cmp_class_f32_e32 vcc, v5, v0
	s_nop 1
	v_cndmask_b32_e32 v5, v6, v5, vcc
	v_div_scale_f32 v6, s[4:5], v5, v5, 1.0
	v_rcp_f32_e32 v7, v6
	s_nop 0
	v_fma_f32 v14, -v6, v7, 1.0
	v_fmac_f32_e32 v7, v14, v7
	v_div_scale_f32 v14, vcc, 1.0, v5, 1.0
	v_mul_f32_e32 v15, v14, v7
	v_fma_f32 v16, -v6, v15, v14
	v_fmac_f32_e32 v15, v16, v7
	v_fma_f32 v6, -v6, v15, v14
	v_div_fmas_f32 v6, v6, v7, v15
	v_div_fixup_f32 v5, v6, v5, 1.0
	global_store_dwordx2 v203, v[4:5], s[6:7]
	s_or_b64 exec, exec, s[8:9]
	s_add_i32 s0, s0, s94
	v_readlane_b32 s4, v252, 28
	v_readlane_b32 s5, v252, 29
	s_nop 1
	s_add_u32 s6, s6, s4
	s_addc_u32 s7, s7, s5
	s_cmpk_lt_i32 s0, 0x4200
	s_cbranch_scc0 .LBB0_579
	s_and_saveexec_b64 s[8:9], s[2:3]
	v_mov_b32_e32 v4, v32
	v_mov_b32_e32 v5, v33
	s_mov_b32 s4, 0x39800000
	v_pk_mul_f32 v[4:5], v[4:5], s[4:5] op_sel_hi:[1,0]
	s_mov_b32 s1, 0xf800000
	v_fma_f32 v5, -v4, v4, v5
	v_add_f32_e32 v5, 0x358637bd, v5
	v_mul_f32_e32 v6, 0x4f800000, v5
	v_cmp_gt_f32_e32 vcc, s1, v5
	s_nop 1
	v_cndmask_b32_e32 v5, v5, v6, vcc
	v_sqrt_f32_e32 v6, v5
	s_nop 0
	v_add_u32_e32 v7, -1, v6
	v_fma_f32 v15, -v7, v6, v5
	v_add_u32_e32 v14, 1, v6
	v_cmp_ge_f32_e64 s[4:5], 0, v15
	s_nop 1
	v_cndmask_b32_e64 v7, v6, v7, s[4:5]
	v_fma_f32 v6, -v14, v6, v5
	v_cmp_lt_f32_e64 s[4:5], 0, v6
	s_nop 1
	v_cndmask_b32_e64 v6, v7, v14, s[4:5]
	v_mul_f32_e32 v7, 0x37800000, v6
	v_cndmask_b32_e32 v6, v6, v7, vcc
	v_cmp_class_f32_e32 vcc, v5, v0
	s_nop 1
	v_cndmask_b32_e32 v5, v6, v5, vcc
	v_div_scale_f32 v6, s[4:5], v5, v5, 1.0
	v_rcp_f32_e32 v7, v6
	s_nop 0
	v_fma_f32 v14, -v6, v7, 1.0
	v_fmac_f32_e32 v7, v14, v7
	v_div_scale_f32 v14, vcc, 1.0, v5, 1.0
	v_mul_f32_e32 v15, v14, v7
	v_fma_f32 v16, -v6, v15, v14
	v_fmac_f32_e32 v15, v16, v7
	v_fma_f32 v6, -v6, v15, v14
	v_div_fmas_f32 v6, v6, v7, v15
	v_div_fixup_f32 v5, v6, v5, 1.0
	global_store_dwordx2 v203, v[4:5], s[6:7]
	s_or_b64 exec, exec, s[8:9]
	s_add_i32 s0, s0, s94
	v_readlane_b32 s4, v252, 28
	v_readlane_b32 s5, v252, 29
	s_nop 1
	s_add_u32 s6, s6, s4
	s_addc_u32 s7, s7, s5
	s_cmpk_lt_i32 s0, 0x4200
	s_cbranch_scc0 .LBB0_579
	s_and_saveexec_b64 s[8:9], s[2:3]
	v_mov_b32_e32 v4, v34
	v_mov_b32_e32 v5, v35
	s_mov_b32 s4, 0x39800000
	v_pk_mul_f32 v[4:5], v[4:5], s[4:5] op_sel_hi:[1,0]
	s_mov_b32 s1, 0xf800000
	v_fma_f32 v5, -v4, v4, v5
	v_add_f32_e32 v5, 0x358637bd, v5
	v_mul_f32_e32 v6, 0x4f800000, v5
	v_cmp_gt_f32_e32 vcc, s1, v5
	s_nop 1
	v_cndmask_b32_e32 v5, v5, v6, vcc
	v_sqrt_f32_e32 v6, v5
	s_nop 0
	v_add_u32_e32 v7, -1, v6
	v_fma_f32 v15, -v7, v6, v5
	v_add_u32_e32 v14, 1, v6
	v_cmp_ge_f32_e64 s[4:5], 0, v15
	s_nop 1
	v_cndmask_b32_e64 v7, v6, v7, s[4:5]
	v_fma_f32 v6, -v14, v6, v5
	v_cmp_lt_f32_e64 s[4:5], 0, v6
	s_nop 1
	v_cndmask_b32_e64 v6, v7, v14, s[4:5]
	v_mul_f32_e32 v7, 0x37800000, v6
	v_cndmask_b32_e32 v6, v6, v7, vcc
	v_cmp_class_f32_e32 vcc, v5, v0
	s_nop 1
	v_cndmask_b32_e32 v5, v6, v5, vcc
	v_div_scale_f32 v6, s[4:5], v5, v5, 1.0
	v_rcp_f32_e32 v7, v6
	s_nop 0
	v_fma_f32 v14, -v6, v7, 1.0
	v_fmac_f32_e32 v7, v14, v7
	v_div_scale_f32 v14, vcc, 1.0, v5, 1.0
	v_mul_f32_e32 v15, v14, v7
	v_fma_f32 v16, -v6, v15, v14
	v_fmac_f32_e32 v15, v16, v7
	v_fma_f32 v6, -v6, v15, v14
	v_div_fmas_f32 v6, v6, v7, v15
	v_div_fixup_f32 v5, v6, v5, 1.0
	global_store_dwordx2 v203, v[4:5], s[6:7]
	s_or_b64 exec, exec, s[8:9]
	s_add_i32 s0, s0, s94
	v_readlane_b32 s4, v252, 28
	v_readlane_b32 s5, v252, 29
	s_nop 1
	s_add_u32 s6, s6, s4
	s_addc_u32 s7, s7, s5
	s_cmpk_lt_i32 s0, 0x4200
	s_cbranch_scc1 .LBB0_577
